# GEMM K-loops: deleted the redundant s_setprio 0/1 flip between the two 16-MFMA halves of each 32-MFMA block (12 sites)
# baseline (speedup 1.0000x reference)
; #define PG8_STAGE(bufoff, gbase, voff) do { _Pragma("unroll") for (int _i = 0; _i < 2; ++_i) \
;         __builtin_amdgcn_global_load_lds((const unsigned*)((const char*)(gbase) + (voff)[_i]), (PG8_LAS unsigned*)(lds + (bufoff) + ldsw + _i * 8192), 16, 0, 0); } while (0)
; #define PG8_LDA(dst, b, h) do { _Pragma("unroll") for (int m = 0; m < 4; ++m) _Pragma("unroll") for (int k = 0; k < 2; ++k) dst[m][k] = *(const PG8_LAS bf16x8*)(lds + PG8_SA(b, h) + aoff + m * 2048 + k * 1024); } while (0)
; #define PG8_LDB(dst, b, h) do { _Pragma("unroll") for (int n = 0; n < 2; ++n) _Pragma("unroll") for (int k = 0; k < 2; ++k) dst[n][k] = *(const PG8_LAS bf16x8*)(lds + PG8_SB(b, h) + boff + n * 2048 + k * 1024); } while (0)
; #define PG8_MMA(ai, bj, At, Bt) do { __builtin_amdgcn_s_setprio(1); _Pragma("unroll") for (int m = 0; m < 4; ++m) _Pragma("unroll") for (int n = 0; n < 2; ++n) _Pragma("unroll") for (int k = 0; k < 2; ++k) \
;         acc[ai][bj][m][n] = __builtin_amdgcn_mfma_f32_16x16x32_bf16(Bt[n][k], At[m][k], acc[ai][bj][m][n], 0, 0, 0); __builtin_amdgcn_s_setprio(0); } while (0)
; #define PG8_WAIT_V(n) asm volatile("s_waitcnt vmcnt(" #n ")" ::: "memory")
; #define PG8_WAIT_L(n) asm volatile("s_waitcnt lgkmcnt(" #n ")" ::: "memory")
; #define PG8_BAR __builtin_amdgcn_s_barrier()
; #define PG8_SCHED __builtin_amdgcn_sched_barrier(0)
; template <class Epi, class Sched, bool ALIGN_EPI = false, bool SP2 = false>
; __device__ __forceinline__ void gemm_phase(PG8_LAS unsigned char* lds, const Gemm g, const Sched& S, const Epi& E) {
;     ...
;             PG8_LDB(B0, 0, 0); PG8_LDB(B1, 0, 1); PG8_SCHED; PG8_LDA(At, 0, 0); PG8_STAGE(PG8_SA(1, 1), a1 + hstep, voffA);
;             PG8_WAIT_V(8); PG8_WAIT_L(0); PG8_BAR; PG8_MMA(0, 0, At, B0); PG8_MMA(0, 1, At, B1); PG8_BAR; PG8_SCHED;
;             PG8_LDA(At, 0, 1); PG8_STAGE(PG8_SB(0, 0), b2, voffB); PG8_STAGE(PG8_SB(0, 1), b2 + hstep, voffB); PG8_STAGE(PG8_SA(0, 0), a2, voffA);
;             PG8_WAIT_V(8); PG8_WAIT_L(0); PG8_BAR; PG8_MMA(1, 0, At, B0); PG8_MMA(1, 1, At, B1); PG8_BAR; PG8_SCHED;
.LBB0_59:
	s_add_i32 s13, s12, 2
	s_add_u32 s14, s0, 0x80
	s_addc_u32 s15, s1, 0
	s_add_i32 s22, 0, 0x10000
	s_cmp_eq_u32 s73, s12
	s_cselect_b32 s21, s5, s15
	s_cselect_b32 s20, s4, s14
	s_cselect_b32 s15, s61, s11
	s_cselect_b32 s14, s60, s10
	s_add_i32 s12, 0, 0x14000
	v_add_u32_e32 v152, s22, v163
	v_add_u32_e32 v160, s12, v163
	ds_read_b128 v[130:133], v152
	ds_read_b128 v[134:137], v152 offset:1024
	ds_read_b128 v[148:151], v152 offset:2048
	ds_read_b128 v[152:155], v152 offset:3072
	ds_read_b128 v[156:159], v160
	ds_read_b128 v[168:171], v160 offset:1024
	ds_read_b128 v[172:175], v160 offset:2048
	ds_read_b128 v[176:179], v160 offset:3072
	v_lshl_add_u64 v[160:161], s[0:1], 0, v[144:145]
	s_add_i32 m0, s66, 0xc000
	ds_read_b128 v[180:183], v167
	ds_read_b128 v[184:187], v167 offset:1024
	ds_read_b128 v[188:191], v167 offset:2048
	ds_read_b128 v[192:195], v167 offset:3072
	ds_read_b128 v[196:199], v167 offset:4096
	ds_read_b128 v[200:203], v167 offset:5120
	ds_read_b128 v[206:209], v167 offset:6144
	ds_read_b128 v[210:213], v167 offset:7168
	global_load_lds_dwordx4 v[160:161], off
	v_lshl_add_u64 v[160:161], s[0:1], 0, v[146:147]
	s_add_i32 m0, s66, 0xe000
	s_nop 0
	global_load_lds_dwordx4 v[160:161], off
	s_waitcnt vmcnt(8)
	s_waitcnt lgkmcnt(0)
	s_barrier
	s_setprio 1
	s_waitcnt lgkmcnt(0)
	v_mfma_f32_16x16x32_bf16 v[126:129], v[130:133], v[180:183], v[126:129]
	v_mfma_f32_16x16x32_bf16 v[122:125], v[148:151], v[180:183], v[122:125]
	v_mfma_f32_16x16x32_bf16 v[110:113], v[130:133], v[188:191], v[110:113]
	v_mfma_f32_16x16x32_bf16 v[106:109], v[148:151], v[188:191], v[106:109]
	v_mfma_f32_16x16x32_bf16 v[94:97], v[130:133], v[196:199], v[94:97]
	v_mfma_f32_16x16x32_bf16 v[90:93], v[148:151], v[196:199], v[90:93]
	v_mfma_f32_16x16x32_bf16 v[78:81], v[130:133], v[206:209], v[78:81]
	v_mfma_f32_16x16x32_bf16 v[74:77], v[148:151], v[206:209], v[74:77]
	v_mfma_f32_16x16x32_bf16 v[126:129], v[134:137], v[184:187], v[126:129]
	v_mfma_f32_16x16x32_bf16 v[122:125], v[152:155], v[184:187], v[122:125]
	v_mfma_f32_16x16x32_bf16 v[110:113], v[134:137], v[192:195], v[110:113]
	v_mfma_f32_16x16x32_bf16 v[106:109], v[152:155], v[192:195], v[106:109]
	v_mfma_f32_16x16x32_bf16 v[94:97], v[134:137], v[200:203], v[94:97]
	v_mfma_f32_16x16x32_bf16 v[90:93], v[152:155], v[200:203], v[90:93]
	v_mfma_f32_16x16x32_bf16 v[78:81], v[134:137], v[210:213], v[78:81]
	v_mfma_f32_16x16x32_bf16 v[74:77], v[152:155], v[210:213], v[74:77]
	v_mfma_f32_16x16x32_bf16 v[118:121], v[156:159], v[180:183], v[118:121]
	v_mfma_f32_16x16x32_bf16 v[114:117], v[172:175], v[180:183], v[114:117]
	v_mfma_f32_16x16x32_bf16 v[102:105], v[156:159], v[188:191], v[102:105]
	v_mfma_f32_16x16x32_bf16 v[98:101], v[172:175], v[188:191], v[98:101]
	v_mfma_f32_16x16x32_bf16 v[86:89], v[156:159], v[196:199], v[86:89]
	v_mfma_f32_16x16x32_bf16 v[82:85], v[172:175], v[196:199], v[82:85]
	v_mfma_f32_16x16x32_bf16 v[70:73], v[156:159], v[206:209], v[70:73]
	v_mfma_f32_16x16x32_bf16 v[66:69], v[172:175], v[206:209], v[66:69]
	v_mfma_f32_16x16x32_bf16 v[118:121], v[168:171], v[184:187], v[118:121]
	v_mfma_f32_16x16x32_bf16 v[114:117], v[176:179], v[184:187], v[114:117]
	v_mfma_f32_16x16x32_bf16 v[102:105], v[168:171], v[192:195], v[102:105]
	v_mfma_f32_16x16x32_bf16 v[98:101], v[176:179], v[192:195], v[98:101]
	v_mfma_f32_16x16x32_bf16 v[86:89], v[168:171], v[200:203], v[86:89]
	v_mfma_f32_16x16x32_bf16 v[82:85], v[176:179], v[200:203], v[82:85]
	v_mfma_f32_16x16x32_bf16 v[70:73], v[168:171], v[210:213], v[70:73]
	v_mfma_f32_16x16x32_bf16 v[66:69], v[176:179], v[210:213], v[66:69]
	s_setprio 0
	s_barrier
	s_add_i32 s22, s22, s30
	v_lshl_add_u64 v[160:161], s[14:15], 0, v[0:1]
	s_mov_b32 m0, s22
	ds_read_b128 v[180:183], v167 offset:16384
	ds_read_b128 v[184:187], v167 offset:17408
	ds_read_b128 v[188:191], v167 offset:18432
	ds_read_b128 v[192:195], v167 offset:19456
	ds_read_b128 v[196:199], v167 offset:20480
	ds_read_b128 v[200:203], v167 offset:21504
	ds_read_b128 v[206:209], v167 offset:22528
	ds_read_b128 v[210:213], v167 offset:23552
	global_load_lds_dwordx4 v[160:161], off
	s_add_i32 m0, s22, 0x2000
	v_lshl_add_u64 v[224:225], s[14:15], 0, v[138:139]
	s_add_u32 s14, s14, s46
	s_addc_u32 s15, s15, 0
	s_add_i32 s12, s12, s30
	global_load_lds_dwordx4 v[224:225], off
	v_lshl_add_u64 v[226:227], s[14:15], 0, v[0:1]
	s_mov_b32 m0, s12
	v_lshl_add_u64 v[228:229], s[14:15], 0, v[138:139]
	global_load_lds_dwordx4 v[226:227], off
	s_add_i32 m0, s12, 0x2000
	v_lshl_add_u64 v[230:231], s[20:21], 0, v[142:143]
	global_load_lds_dwordx4 v[228:229], off
	s_mov_b32 m0, s66
	v_lshl_add_u64 v[232:233], s[20:21], 0, v[140:141]
	global_load_lds_dwordx4 v[230:231], off
	s_mov_b32 m0, s67
	s_nop 0
	global_load_lds_dwordx4 v[232:233], off
	s_waitcnt vmcnt(8)
	s_waitcnt lgkmcnt(0)
	s_barrier
; #define PG8_STAGE(bufoff, gbase, voff) do { _Pragma("unroll") for (int _i = 0; _i < 2; ++_i) \
;         __builtin_amdgcn_global_load_lds((const unsigned*)((const char*)(gbase) + (voff)[_i]), (PG8_LAS unsigned*)(lds + (bufoff) + ldsw + _i * 8192), 16, 0, 0); } while (0)
; #define PG8_LDA(dst, b, h) do { _Pragma("unroll") for (int m = 0; m < 4; ++m) _Pragma("unroll") for (int k = 0; k < 2; ++k) dst[m][k] = *(const PG8_LAS bf16x8*)(lds + PG8_SA(b, h) + aoff + m * 2048 + k * 1024); } while (0)
; #define PG8_LDB(dst, b, h) do { _Pragma("unroll") for (int n = 0; n < 2; ++n) _Pragma("unroll") for (int k = 0; k < 2; ++k) dst[n][k] = *(const PG8_LAS bf16x8*)(lds + PG8_SB(b, h) + boff + n * 2048 + k * 1024); } while (0)
; #define PG8_MMA(ai, bj, At, Bt) do { __builtin_amdgcn_s_setprio(1); _Pragma("unroll") for (int m = 0; m < 4; ++m) _Pragma("unroll") for (int n = 0; n < 2; ++n) _Pragma("unroll") for (int k = 0; k < 2; ++k) \
;         acc[ai][bj][m][n] = __builtin_amdgcn_mfma_f32_16x16x32_bf16(Bt[n][k], At[m][k], acc[ai][bj][m][n], 0, 0, 0); __builtin_amdgcn_s_setprio(0); } while (0)
; #define PG8_WAIT_V(n) asm volatile("s_waitcnt vmcnt(" #n ")" ::: "memory")
; #define PG8_WAIT_L(n) asm volatile("s_waitcnt lgkmcnt(" #n ")" ::: "memory")
; #define PG8_BAR __builtin_amdgcn_s_barrier()
; #define PG8_SCHED __builtin_amdgcn_sched_barrier(0)
; template <class Epi, class Sched, bool ALIGN_EPI = false, bool SP2 = false>
; __device__ __forceinline__ void gemm_phase(PG8_LAS unsigned char* lds, const Gemm g, const Sched& S, const Epi& E) {
;     ...
;             PG8_WAIT_V(8); PG8_WAIT_L(0); PG8_BAR; PG8_MMA(1, 0, At, B0); PG8_MMA(1, 1, At, B1); PG8_BAR; PG8_SCHED;
;             PG8_LDB(B0, 1, 0); PG8_LDB(B1, 1, 1); PG8_SCHED; PG8_LDA(At, 1, 0); PG8_STAGE(PG8_SA(0, 1), a2 + hstep, voffA);
;             PG8_WAIT_V(8); PG8_WAIT_L(0); PG8_BAR; PG8_MMA(0, 0, At, B0); PG8_MMA(0, 1, At, B1); PG8_BAR; PG8_SCHED;
	s_setprio 1
	s_waitcnt lgkmcnt(0)
	v_mfma_f32_16x16x32_bf16 v[62:65], v[130:133], v[180:183], v[62:65]
	v_mfma_f32_16x16x32_bf16 v[58:61], v[148:151], v[180:183], v[58:61]
	v_mfma_f32_16x16x32_bf16 v[46:49], v[130:133], v[188:191], v[46:49]
	v_mfma_f32_16x16x32_bf16 v[42:45], v[148:151], v[188:191], v[42:45]
	v_mfma_f32_16x16x32_bf16 v[30:33], v[130:133], v[196:199], v[30:33]
	v_mfma_f32_16x16x32_bf16 v[26:29], v[148:151], v[196:199], v[26:29]
	v_mfma_f32_16x16x32_bf16 v[14:17], v[130:133], v[206:209], v[14:17]
	v_mfma_f32_16x16x32_bf16 v[10:13], v[148:151], v[206:209], v[10:13]
	v_mfma_f32_16x16x32_bf16 v[62:65], v[134:137], v[184:187], v[62:65]
	v_mfma_f32_16x16x32_bf16 v[58:61], v[152:155], v[184:187], v[58:61]
	v_mfma_f32_16x16x32_bf16 v[46:49], v[134:137], v[192:195], v[46:49]
	v_mfma_f32_16x16x32_bf16 v[42:45], v[152:155], v[192:195], v[42:45]
	v_mfma_f32_16x16x32_bf16 v[30:33], v[134:137], v[200:203], v[30:33]
	v_mfma_f32_16x16x32_bf16 v[26:29], v[152:155], v[200:203], v[26:29]
	v_mfma_f32_16x16x32_bf16 v[14:17], v[134:137], v[210:213], v[14:17]
	v_mfma_f32_16x16x32_bf16 v[10:13], v[152:155], v[210:213], v[10:13]
	v_mfma_f32_16x16x32_bf16 v[54:57], v[156:159], v[180:183], v[54:57]
	v_mfma_f32_16x16x32_bf16 v[50:53], v[172:175], v[180:183], v[50:53]
	v_mfma_f32_16x16x32_bf16 v[38:41], v[156:159], v[188:191], v[38:41]
	v_mfma_f32_16x16x32_bf16 v[34:37], v[172:175], v[188:191], v[34:37]
	v_mfma_f32_16x16x32_bf16 v[22:25], v[156:159], v[196:199], v[22:25]
	v_mfma_f32_16x16x32_bf16 v[18:21], v[172:175], v[196:199], v[18:21]
	v_mfma_f32_16x16x32_bf16 v[6:9], v[156:159], v[206:209], v[6:9]
	v_mfma_f32_16x16x32_bf16 v[2:5], v[172:175], v[206:209], v[2:5]
	v_mfma_f32_16x16x32_bf16 v[54:57], v[168:171], v[184:187], v[54:57]
	v_mfma_f32_16x16x32_bf16 v[50:53], v[176:179], v[184:187], v[50:53]
	v_mfma_f32_16x16x32_bf16 v[38:41], v[168:171], v[192:195], v[38:41]
	v_mfma_f32_16x16x32_bf16 v[34:37], v[176:179], v[192:195], v[34:37]
	v_mfma_f32_16x16x32_bf16 v[22:25], v[168:171], v[200:203], v[22:25]
	v_mfma_f32_16x16x32_bf16 v[18:21], v[176:179], v[200:203], v[18:21]
	v_mfma_f32_16x16x32_bf16 v[6:9], v[168:171], v[210:213], v[6:9]
	v_mfma_f32_16x16x32_bf16 v[2:5], v[176:179], v[210:213], v[2:5]
	s_setprio 0
	s_barrier
	s_add_i32 s12, 0, 0x18000
	s_add_i32 s22, 0, 0x1c000
	v_add_u32_e32 v152, s12, v163
	v_add_u32_e32 v176, s22, v163
	ds_read_b128 v[130:133], v152
	ds_read_b128 v[134:137], v152 offset:1024
	ds_read_b128 v[148:151], v152 offset:2048
	ds_read_b128 v[152:155], v152 offset:3072
	ds_read_b128 v[156:159], v176
	ds_read_b128 v[168:171], v176 offset:1024
	ds_read_b128 v[172:175], v176 offset:2048
	ds_read_b128 v[176:179], v176 offset:3072
	s_add_u32 s14, s20, s46
	s_addc_u32 s15, s21, 0
	s_mov_b32 m0, s68
	v_lshl_add_u64 v[234:235], s[14:15], 0, v[142:143]
	ds_read_b128 v[180:183], v167 offset:32768
	ds_read_b128 v[184:187], v167 offset:33792
	ds_read_b128 v[188:191], v167 offset:34816
	ds_read_b128 v[192:195], v167 offset:35840
	ds_read_b128 v[196:199], v167 offset:36864
	ds_read_b128 v[200:203], v167 offset:37888
	ds_read_b128 v[206:209], v167 offset:38912
	ds_read_b128 v[210:213], v167 offset:39936
	global_load_lds_dwordx4 v[234:235], off
	v_lshl_add_u64 v[234:235], s[14:15], 0, v[140:141]
	s_mov_b32 m0, s69
	s_nop 0
	global_load_lds_dwordx4 v[234:235], off
	s_waitcnt vmcnt(8)
	s_waitcnt lgkmcnt(0)
	s_barrier
	s_setprio 1
	s_waitcnt lgkmcnt(0)
	v_mfma_f32_16x16x32_bf16 v[126:129], v[130:133], v[180:183], v[126:129]
	v_mfma_f32_16x16x32_bf16 v[122:125], v[148:151], v[180:183], v[122:125]
	v_mfma_f32_16x16x32_bf16 v[110:113], v[130:133], v[188:191], v[110:113]
	v_mfma_f32_16x16x32_bf16 v[106:109], v[148:151], v[188:191], v[106:109]
	v_mfma_f32_16x16x32_bf16 v[94:97], v[130:133], v[196:199], v[94:97]
	v_mfma_f32_16x16x32_bf16 v[90:93], v[148:151], v[196:199], v[90:93]
	v_mfma_f32_16x16x32_bf16 v[78:81], v[130:133], v[206:209], v[78:81]
	v_mfma_f32_16x16x32_bf16 v[74:77], v[148:151], v[206:209], v[74:77]
	v_mfma_f32_16x16x32_bf16 v[126:129], v[134:137], v[184:187], v[126:129]
	v_mfma_f32_16x16x32_bf16 v[122:125], v[152:155], v[184:187], v[122:125]
	v_mfma_f32_16x16x32_bf16 v[110:113], v[134:137], v[192:195], v[110:113]
	v_mfma_f32_16x16x32_bf16 v[106:109], v[152:155], v[192:195], v[106:109]
	v_mfma_f32_16x16x32_bf16 v[94:97], v[134:137], v[200:203], v[94:97]
	v_mfma_f32_16x16x32_bf16 v[90:93], v[152:155], v[200:203], v[90:93]
	v_mfma_f32_16x16x32_bf16 v[78:81], v[134:137], v[210:213], v[78:81]
	v_mfma_f32_16x16x32_bf16 v[74:77], v[152:155], v[210:213], v[74:77]
	v_mfma_f32_16x16x32_bf16 v[118:121], v[156:159], v[180:183], v[118:121]
	v_mfma_f32_16x16x32_bf16 v[114:117], v[172:175], v[180:183], v[114:117]
	v_mfma_f32_16x16x32_bf16 v[102:105], v[156:159], v[188:191], v[102:105]
	v_mfma_f32_16x16x32_bf16 v[98:101], v[172:175], v[188:191], v[98:101]
	v_mfma_f32_16x16x32_bf16 v[86:89], v[156:159], v[196:199], v[86:89]
	v_mfma_f32_16x16x32_bf16 v[82:85], v[172:175], v[196:199], v[82:85]
	v_mfma_f32_16x16x32_bf16 v[70:73], v[156:159], v[206:209], v[70:73]
	v_mfma_f32_16x16x32_bf16 v[66:69], v[172:175], v[206:209], v[66:69]
	v_mfma_f32_16x16x32_bf16 v[118:121], v[168:171], v[184:187], v[118:121]
	v_mfma_f32_16x16x32_bf16 v[114:117], v[176:179], v[184:187], v[114:117]
	v_mfma_f32_16x16x32_bf16 v[102:105], v[168:171], v[192:195], v[102:105]
	v_mfma_f32_16x16x32_bf16 v[98:101], v[176:179], v[192:195], v[98:101]
	v_mfma_f32_16x16x32_bf16 v[86:89], v[168:171], v[200:203], v[86:89]
	v_mfma_f32_16x16x32_bf16 v[82:85], v[176:179], v[200:203], v[82:85]
	v_mfma_f32_16x16x32_bf16 v[70:73], v[168:171], v[210:213], v[70:73]
	v_mfma_f32_16x16x32_bf16 v[66:69], v[176:179], v[210:213], v[66:69]
	s_setprio 0
	s_barrier
; #define PG8_STAGE(bufoff, gbase, voff) do { _Pragma("unroll") for (int _i = 0; _i < 2; ++_i) \
;         __builtin_amdgcn_global_load_lds((const unsigned*)((const char*)(gbase) + (voff)[_i]), (PG8_LAS unsigned*)(lds + (bufoff) + ldsw + _i * 8192), 16, 0, 0); } while (0)
; #define PG8_LDA(dst, b, h) do { _Pragma("unroll") for (int m = 0; m < 4; ++m) _Pragma("unroll") for (int k = 0; k < 2; ++k) dst[m][k] = *(const PG8_LAS bf16x8*)(lds + PG8_SA(b, h) + aoff + m * 2048 + k * 1024); } while (0)
; #define PG8_MMA(ai, bj, At, Bt) do { __builtin_amdgcn_s_setprio(1); _Pragma("unroll") for (int m = 0; m < 4; ++m) _Pragma("unroll") for (int n = 0; n < 2; ++n) _Pragma("unroll") for (int k = 0; k < 2; ++k) \
;         acc[ai][bj][m][n] = __builtin_amdgcn_mfma_f32_16x16x32_bf16(Bt[n][k], At[m][k], acc[ai][bj][m][n], 0, 0, 0); __builtin_amdgcn_s_setprio(0); } while (0)
; #define PG8_WAIT_V(n) asm volatile("s_waitcnt vmcnt(" #n ")" ::: "memory")
; #define PG8_WAIT_L(n) asm volatile("s_waitcnt lgkmcnt(" #n ")" ::: "memory")
; #define PG8_BAR __builtin_amdgcn_s_barrier()
; #define PG8_SCHED __builtin_amdgcn_sched_barrier(0)
; template <class Epi, class Sched, bool ALIGN_EPI = false, bool SP2 = false>
; __device__ __forceinline__ void gemm_phase(PG8_LAS unsigned char* lds, const Gemm g, const Sched& S, const Epi& E) {
;     ...
;             PG8_LDA(At, 1, 1); PG8_STAGE(PG8_SB(1, 0), b3, voffB); PG8_STAGE(PG8_SB(1, 1), b3 + hstep, voffB); PG8_STAGE(PG8_SA(1, 0), a3, voffA);
;             PG8_WAIT_V(8); PG8_WAIT_L(0); PG8_BAR; PG8_MMA(1, 0, At, B0); PG8_MMA(1, 1, At, B1); PG8_BAR; PG8_SCHED;
	s_add_i32 s12, s12, s30
	v_lshl_add_u64 v[160:161], v[160:161], 0, s[24:25]
	s_mov_b32 m0, s12
	ds_read_b128 v[180:183], v167 offset:49152
	ds_read_b128 v[184:187], v167 offset:50176
	ds_read_b128 v[188:191], v167 offset:51200
	ds_read_b128 v[192:195], v167 offset:52224
	ds_read_b128 v[196:199], v167 offset:53248
	ds_read_b128 v[200:203], v167 offset:54272
	ds_read_b128 v[206:209], v167 offset:55296
	ds_read_b128 v[210:213], v167 offset:56320
	global_load_lds_dwordx4 v[160:161], off
	v_lshl_add_u64 v[160:161], v[224:225], 0, s[24:25]
	s_add_i32 m0, s12, 0x2000
	s_add_i32 s12, s22, s30
	global_load_lds_dwordx4 v[160:161], off
	v_lshl_add_u64 v[160:161], v[226:227], 0, s[24:25]
	s_mov_b32 m0, s12
	s_nop 0
	global_load_lds_dwordx4 v[160:161], off
	v_lshl_add_u64 v[160:161], v[228:229], 0, s[24:25]
	s_add_i32 m0, s12, 0x2000
	s_nop 0
	global_load_lds_dwordx4 v[160:161], off
	v_lshl_add_u64 v[160:161], v[230:231], 0, s[24:25]
	s_mov_b32 m0, s74
	s_nop 0
	global_load_lds_dwordx4 v[160:161], off
	v_lshl_add_u64 v[160:161], v[232:233], 0, s[24:25]
	s_mov_b32 m0, s75
	s_nop 0
	global_load_lds_dwordx4 v[160:161], off
	s_waitcnt vmcnt(8)
	s_waitcnt lgkmcnt(0)
	s_barrier
	s_setprio 1
	s_waitcnt lgkmcnt(0)
	v_mfma_f32_16x16x32_bf16 v[62:65], v[130:133], v[180:183], v[62:65]
	v_mfma_f32_16x16x32_bf16 v[58:61], v[148:151], v[180:183], v[58:61]
	v_mfma_f32_16x16x32_bf16 v[46:49], v[130:133], v[188:191], v[46:49]
	v_mfma_f32_16x16x32_bf16 v[42:45], v[148:151], v[188:191], v[42:45]
	v_mfma_f32_16x16x32_bf16 v[30:33], v[130:133], v[196:199], v[30:33]
	v_mfma_f32_16x16x32_bf16 v[26:29], v[148:151], v[196:199], v[26:29]
	v_mfma_f32_16x16x32_bf16 v[14:17], v[130:133], v[206:209], v[14:17]
	v_mfma_f32_16x16x32_bf16 v[10:13], v[148:151], v[206:209], v[10:13]
	v_mfma_f32_16x16x32_bf16 v[62:65], v[134:137], v[184:187], v[62:65]
	v_mfma_f32_16x16x32_bf16 v[58:61], v[152:155], v[184:187], v[58:61]
	v_mfma_f32_16x16x32_bf16 v[46:49], v[134:137], v[192:195], v[46:49]
	v_mfma_f32_16x16x32_bf16 v[42:45], v[152:155], v[192:195], v[42:45]
	v_mfma_f32_16x16x32_bf16 v[30:33], v[134:137], v[200:203], v[30:33]
	v_mfma_f32_16x16x32_bf16 v[26:29], v[152:155], v[200:203], v[26:29]
	v_mfma_f32_16x16x32_bf16 v[14:17], v[134:137], v[210:213], v[14:17]
	v_mfma_f32_16x16x32_bf16 v[10:13], v[152:155], v[210:213], v[10:13]
	v_mfma_f32_16x16x32_bf16 v[54:57], v[156:159], v[180:183], v[54:57]
	v_mfma_f32_16x16x32_bf16 v[50:53], v[172:175], v[180:183], v[50:53]
	v_mfma_f32_16x16x32_bf16 v[38:41], v[156:159], v[188:191], v[38:41]
	v_mfma_f32_16x16x32_bf16 v[34:37], v[172:175], v[188:191], v[34:37]
	v_mfma_f32_16x16x32_bf16 v[22:25], v[156:159], v[196:199], v[22:25]
	v_mfma_f32_16x16x32_bf16 v[18:21], v[172:175], v[196:199], v[18:21]
	v_mfma_f32_16x16x32_bf16 v[6:9], v[156:159], v[206:209], v[6:9]
	v_mfma_f32_16x16x32_bf16 v[2:5], v[172:175], v[206:209], v[2:5]
	v_mfma_f32_16x16x32_bf16 v[54:57], v[168:171], v[184:187], v[54:57]
	v_mfma_f32_16x16x32_bf16 v[50:53], v[176:179], v[184:187], v[50:53]
	v_mfma_f32_16x16x32_bf16 v[38:41], v[168:171], v[192:195], v[38:41]
	v_mfma_f32_16x16x32_bf16 v[34:37], v[176:179], v[192:195], v[34:37]
	v_mfma_f32_16x16x32_bf16 v[22:25], v[168:171], v[200:203], v[22:25]
	v_mfma_f32_16x16x32_bf16 v[18:21], v[176:179], v[200:203], v[18:21]
	v_mfma_f32_16x16x32_bf16 v[6:9], v[168:171], v[210:213], v[6:9]
	v_mfma_f32_16x16x32_bf16 v[2:5], v[176:179], v[210:213], v[2:5]
	s_setprio 0
	s_barrier
	s_add_u32 s0, s0, 0x100
	s_addc_u32 s1, s1, 0
	s_add_u32 s10, s10, 0x100
	s_addc_u32 s11, s11, 0
	s_cmp_ge_u32 s13, s72
	s_mov_b32 s12, s13
	s_cbranch_scc0 .LBB0_59
	s_and_b64 vcc, exec, s[58:59]
	s_cbranch_vccz .LBB0_62
	s_barrier

; #define PG8_STAGE(bufoff, gbase, voff) do { _Pragma("unroll") for (int _i = 0; _i < 2; ++_i) \
;         __builtin_amdgcn_global_load_lds((const unsigned*)((const char*)(gbase) + (voff)[_i]), (PG8_LAS unsigned*)(lds + (bufoff) + ldsw + _i * 8192), 16, 0, 0); } while (0)
; #define PG8_LDA(dst, b, h) do { _Pragma("unroll") for (int m = 0; m < 4; ++m) _Pragma("unroll") for (int k = 0; k < 2; ++k) dst[m][k] = *(const PG8_LAS bf16x8*)(lds + PG8_SA(b, h) + aoff + m * 2048 + k * 1024); } while (0)
; #define PG8_LDB(dst, b, h) do { _Pragma("unroll") for (int n = 0; n < 2; ++n) _Pragma("unroll") for (int k = 0; k < 2; ++k) dst[n][k] = *(const PG8_LAS bf16x8*)(lds + PG8_SB(b, h) + boff + n * 2048 + k * 1024); } while (0)
; #define PG8_MMA(ai, bj, At, Bt) do { __builtin_amdgcn_s_setprio(1); _Pragma("unroll") for (int m = 0; m < 4; ++m) _Pragma("unroll") for (int n = 0; n < 2; ++n) _Pragma("unroll") for (int k = 0; k < 2; ++k) \
;         acc[ai][bj][m][n] = __builtin_amdgcn_mfma_f32_16x16x32_bf16(Bt[n][k], At[m][k], acc[ai][bj][m][n], 0, 0, 0); __builtin_amdgcn_s_setprio(0); } while (0)
; #define PG8_WAIT_V(n) asm volatile("s_waitcnt vmcnt(" #n ")" ::: "memory")
; #define PG8_WAIT_L(n) asm volatile("s_waitcnt lgkmcnt(" #n ")" ::: "memory")
; #define PG8_BAR __builtin_amdgcn_s_barrier()
; #define PG8_SCHED __builtin_amdgcn_sched_barrier(0)
; template <class Epi, class Sched, bool ALIGN_EPI = false, bool SP2 = false>
; __device__ __forceinline__ void gemm_phase(PG8_LAS unsigned char* lds, const Gemm g, const Sched& S, const Epi& E) {
;     ...
;             PG8_LDB(B0, 0, 0); PG8_LDB(B1, 0, 1); PG8_SCHED; PG8_LDA(At, 0, 0); PG8_STAGE(PG8_SA(1, 1), a1 + hstep, voffA);
;             PG8_WAIT_V(8); PG8_WAIT_L(0); PG8_BAR; PG8_MMA(0, 0, At, B0); PG8_MMA(0, 1, At, B1); PG8_BAR; PG8_SCHED;
;             PG8_LDA(At, 0, 1); PG8_STAGE(PG8_SB(0, 0), b2, voffB); PG8_STAGE(PG8_SB(0, 1), b2 + hstep, voffB); PG8_STAGE(PG8_SA(0, 0), a2, voffA);
;             PG8_WAIT_V(8); PG8_WAIT_L(0); PG8_BAR; PG8_MMA(1, 0, At, B0); PG8_MMA(1, 1, At, B1); PG8_BAR; PG8_SCHED;
.LBB0_535:
	s_add_u32 s4, s0, 0xfffc0080
	s_addc_u32 s5, s1, -1
	s_add_i32 s14, 0, 0x10000
	s_cmp_eq_u32 s35, 12
	s_cselect_b32 s21, s10, s5
	s_cselect_b32 s20, s11, s4
	v_add_u32_e32 v146, s14, v148
	s_cselect_b32 s5, s12, s34
	s_cselect_b32 s4, s13, s29
	s_add_i32 s41, 0, 0x14000
	ds_read_b128 v[142:145], v146
	ds_read_b128 v[154:157], v146 offset:1024
	ds_read_b128 v[158:161], v146 offset:2048
	ds_read_b128 v[162:165], v146 offset:3072
	v_add_u32_e32 v146, s41, v148
	ds_read_b128 v[166:169], v146
	ds_read_b128 v[170:173], v146 offset:1024
	ds_read_b128 v[174:177], v146 offset:2048
	ds_read_b128 v[178:181], v146 offset:3072
	v_lshl_add_u64 v[202:203], s[0:1], 0, v[138:139]
	s_add_i32 m0, s30, 0xc000
	ds_read_b128 v[182:185], v152
	ds_read_b128 v[186:189], v152 offset:1024
	ds_read_b128 v[190:193], v152 offset:2048
	ds_read_b128 v[194:197], v152 offset:3072
	ds_read_b128 v[198:201], v152 offset:4096
	ds_read_b128 v[206:209], v152 offset:5120
	ds_read_b128 v[210:213], v152 offset:6144
	ds_read_b128 v[224:227], v152 offset:7168
	global_load_lds_dwordx4 v[202:203], off
	v_lshl_add_u64 v[202:203], s[0:1], 0, v[140:141]
	s_add_i32 m0, s30, 0xe000
	s_nop 0
	global_load_lds_dwordx4 v[202:203], off
	s_waitcnt vmcnt(8)
	s_waitcnt lgkmcnt(0)
	s_barrier
	s_setprio 1
	s_waitcnt lgkmcnt(0)
	v_mfma_f32_16x16x32_bf16 v[126:129], v[142:145], v[182:185], v[126:129]
	v_mfma_f32_16x16x32_bf16 v[118:121], v[158:161], v[182:185], v[118:121]
	v_mfma_f32_16x16x32_bf16 v[110:113], v[142:145], v[190:193], v[110:113]
	v_mfma_f32_16x16x32_bf16 v[102:105], v[158:161], v[190:193], v[102:105]
	v_mfma_f32_16x16x32_bf16 v[94:97], v[142:145], v[198:201], v[94:97]
	v_mfma_f32_16x16x32_bf16 v[86:89], v[158:161], v[198:201], v[86:89]
	v_mfma_f32_16x16x32_bf16 v[78:81], v[142:145], v[210:213], v[78:81]
	v_mfma_f32_16x16x32_bf16 v[70:73], v[158:161], v[210:213], v[70:73]
	v_mfma_f32_16x16x32_bf16 v[126:129], v[154:157], v[186:189], v[126:129]
	v_mfma_f32_16x16x32_bf16 v[118:121], v[162:165], v[186:189], v[118:121]
	v_mfma_f32_16x16x32_bf16 v[110:113], v[154:157], v[194:197], v[110:113]
	v_mfma_f32_16x16x32_bf16 v[102:105], v[162:165], v[194:197], v[102:105]
	v_mfma_f32_16x16x32_bf16 v[94:97], v[154:157], v[206:209], v[94:97]
	v_mfma_f32_16x16x32_bf16 v[86:89], v[162:165], v[206:209], v[86:89]
	v_mfma_f32_16x16x32_bf16 v[78:81], v[154:157], v[224:227], v[78:81]
	v_mfma_f32_16x16x32_bf16 v[70:73], v[162:165], v[224:227], v[70:73]
	v_mfma_f32_16x16x32_bf16 v[122:125], v[166:169], v[182:185], v[122:125]
	v_mfma_f32_16x16x32_bf16 v[114:117], v[174:177], v[182:185], v[114:117]
	v_mfma_f32_16x16x32_bf16 v[106:109], v[166:169], v[190:193], v[106:109]
	v_mfma_f32_16x16x32_bf16 v[98:101], v[174:177], v[190:193], v[98:101]
	v_mfma_f32_16x16x32_bf16 v[90:93], v[166:169], v[198:201], v[90:93]
	v_mfma_f32_16x16x32_bf16 v[82:85], v[174:177], v[198:201], v[82:85]
	v_mfma_f32_16x16x32_bf16 v[74:77], v[166:169], v[210:213], v[74:77]
	v_mfma_f32_16x16x32_bf16 v[66:69], v[174:177], v[210:213], v[66:69]
	v_mfma_f32_16x16x32_bf16 v[122:125], v[170:173], v[186:189], v[122:125]
	v_mfma_f32_16x16x32_bf16 v[114:117], v[178:181], v[186:189], v[114:117]
	v_mfma_f32_16x16x32_bf16 v[106:109], v[170:173], v[194:197], v[106:109]
	v_mfma_f32_16x16x32_bf16 v[98:101], v[178:181], v[194:197], v[98:101]
	v_mfma_f32_16x16x32_bf16 v[90:93], v[170:173], v[206:209], v[90:93]
	v_mfma_f32_16x16x32_bf16 v[82:85], v[178:181], v[206:209], v[82:85]
	v_mfma_f32_16x16x32_bf16 v[74:77], v[170:173], v[224:227], v[74:77]
	v_mfma_f32_16x16x32_bf16 v[66:69], v[178:181], v[224:227], v[66:69]
	s_setprio 0
	s_barrier
	s_add_i32 s14, s14, s22
	v_lshl_add_u64 v[202:203], s[4:5], 0, v[0:1]
	s_mov_b32 m0, s14
	ds_read_b128 v[182:185], v152 offset:16384
	ds_read_b128 v[186:189], v152 offset:17408
	ds_read_b128 v[190:193], v152 offset:18432
	ds_read_b128 v[194:197], v152 offset:19456
	ds_read_b128 v[198:201], v152 offset:20480
	ds_read_b128 v[206:209], v152 offset:21504
	ds_read_b128 v[210:213], v152 offset:22528
	ds_read_b128 v[224:227], v152 offset:23552
	global_load_lds_dwordx4 v[202:203], off
	s_add_i32 m0, s14, 0x2000
	s_add_u32 s14, s4, 0x40000
	v_lshl_add_u64 v[228:229], s[4:5], 0, v[130:131]
	s_addc_u32 s15, s5, 0
	s_add_i32 s41, s41, s22
	global_load_lds_dwordx4 v[228:229], off
	v_lshl_add_u64 v[230:231], s[14:15], 0, v[0:1]
	s_mov_b32 m0, s41
	v_lshl_add_u64 v[232:233], s[20:21], 0, v[132:133]
	global_load_lds_dwordx4 v[230:231], off
	v_lshl_add_u64 v[230:231], s[14:15], 0, v[130:131]
	s_add_i32 m0, s41, 0x2000
	s_nop 0
	global_load_lds_dwordx4 v[230:231], off
	v_lshl_add_u64 v[230:231], s[20:21], 0, v[134:135]
	s_mov_b32 m0, s30
	s_nop 0
	global_load_lds_dwordx4 v[230:231], off
	s_mov_b32 m0, s31
	s_nop 0
	global_load_lds_dwordx4 v[232:233], off
	s_waitcnt vmcnt(8)
	s_waitcnt lgkmcnt(0)
	s_barrier
; #define PG8_STAGE(bufoff, gbase, voff) do { _Pragma("unroll") for (int _i = 0; _i < 2; ++_i) \
;         __builtin_amdgcn_global_load_lds((const unsigned*)((const char*)(gbase) + (voff)[_i]), (PG8_LAS unsigned*)(lds + (bufoff) + ldsw + _i * 8192), 16, 0, 0); } while (0)
; #define PG8_LDA(dst, b, h) do { _Pragma("unroll") for (int m = 0; m < 4; ++m) _Pragma("unroll") for (int k = 0; k < 2; ++k) dst[m][k] = *(const PG8_LAS bf16x8*)(lds + PG8_SA(b, h) + aoff + m * 2048 + k * 1024); } while (0)
; #define PG8_LDB(dst, b, h) do { _Pragma("unroll") for (int n = 0; n < 2; ++n) _Pragma("unroll") for (int k = 0; k < 2; ++k) dst[n][k] = *(const PG8_LAS bf16x8*)(lds + PG8_SB(b, h) + boff + n * 2048 + k * 1024); } while (0)
; #define PG8_MMA(ai, bj, At, Bt) do { __builtin_amdgcn_s_setprio(1); _Pragma("unroll") for (int m = 0; m < 4; ++m) _Pragma("unroll") for (int n = 0; n < 2; ++n) _Pragma("unroll") for (int k = 0; k < 2; ++k) \
;         acc[ai][bj][m][n] = __builtin_amdgcn_mfma_f32_16x16x32_bf16(Bt[n][k], At[m][k], acc[ai][bj][m][n], 0, 0, 0); __builtin_amdgcn_s_setprio(0); } while (0)
; #define PG8_WAIT_V(n) asm volatile("s_waitcnt vmcnt(" #n ")" ::: "memory")
; #define PG8_WAIT_L(n) asm volatile("s_waitcnt lgkmcnt(" #n ")" ::: "memory")
; #define PG8_BAR __builtin_amdgcn_s_barrier()
; #define PG8_SCHED __builtin_amdgcn_sched_barrier(0)
; template <class Epi, class Sched, bool ALIGN_EPI = false, bool SP2 = false>
; __device__ __forceinline__ void gemm_phase(PG8_LAS unsigned char* lds, const Gemm g, const Sched& S, const Epi& E) {
;     ...
;             PG8_WAIT_V(8); PG8_WAIT_L(0); PG8_BAR; PG8_MMA(1, 0, At, B0); PG8_MMA(1, 1, At, B1); PG8_BAR; PG8_SCHED;
;             PG8_LDB(B0, 1, 0); PG8_LDB(B1, 1, 1); PG8_SCHED; PG8_LDA(At, 1, 0); PG8_STAGE(PG8_SA(0, 1), a2 + hstep, voffA);
;             PG8_WAIT_V(8); PG8_WAIT_L(0); PG8_BAR; PG8_MMA(0, 0, At, B0); PG8_MMA(0, 1, At, B1); PG8_BAR; PG8_SCHED;
	s_setprio 1
	s_waitcnt lgkmcnt(0)
	v_mfma_f32_16x16x32_bf16 v[62:65], v[142:145], v[182:185], v[62:65]
	v_mfma_f32_16x16x32_bf16 v[54:57], v[158:161], v[182:185], v[54:57]
	v_mfma_f32_16x16x32_bf16 v[46:49], v[142:145], v[190:193], v[46:49]
	v_mfma_f32_16x16x32_bf16 v[38:41], v[158:161], v[190:193], v[38:41]
	v_mfma_f32_16x16x32_bf16 v[30:33], v[142:145], v[198:201], v[30:33]
	v_mfma_f32_16x16x32_bf16 v[22:25], v[158:161], v[198:201], v[22:25]
	v_mfma_f32_16x16x32_bf16 v[14:17], v[142:145], v[210:213], v[14:17]
	v_mfma_f32_16x16x32_bf16 v[6:9], v[158:161], v[210:213], v[6:9]
	v_mfma_f32_16x16x32_bf16 v[62:65], v[154:157], v[186:189], v[62:65]
	v_mfma_f32_16x16x32_bf16 v[54:57], v[162:165], v[186:189], v[54:57]
	v_mfma_f32_16x16x32_bf16 v[46:49], v[154:157], v[194:197], v[46:49]
	v_mfma_f32_16x16x32_bf16 v[38:41], v[162:165], v[194:197], v[38:41]
	v_mfma_f32_16x16x32_bf16 v[30:33], v[154:157], v[206:209], v[30:33]
	v_mfma_f32_16x16x32_bf16 v[22:25], v[162:165], v[206:209], v[22:25]
	v_mfma_f32_16x16x32_bf16 v[14:17], v[154:157], v[224:227], v[14:17]
	v_mfma_f32_16x16x32_bf16 v[6:9], v[162:165], v[224:227], v[6:9]
	v_mfma_f32_16x16x32_bf16 v[58:61], v[166:169], v[182:185], v[58:61]
	v_mfma_f32_16x16x32_bf16 v[50:53], v[174:177], v[182:185], v[50:53]
	v_mfma_f32_16x16x32_bf16 v[42:45], v[166:169], v[190:193], v[42:45]
	v_mfma_f32_16x16x32_bf16 v[34:37], v[174:177], v[190:193], v[34:37]
	v_mfma_f32_16x16x32_bf16 v[26:29], v[166:169], v[198:201], v[26:29]
	v_mfma_f32_16x16x32_bf16 v[18:21], v[174:177], v[198:201], v[18:21]
	v_mfma_f32_16x16x32_bf16 v[10:13], v[166:169], v[210:213], v[10:13]
	v_mfma_f32_16x16x32_bf16 v[2:5], v[174:177], v[210:213], v[2:5]
	v_mfma_f32_16x16x32_bf16 v[58:61], v[170:173], v[186:189], v[58:61]
	v_mfma_f32_16x16x32_bf16 v[50:53], v[178:181], v[186:189], v[50:53]
	v_mfma_f32_16x16x32_bf16 v[42:45], v[170:173], v[194:197], v[42:45]
	v_mfma_f32_16x16x32_bf16 v[34:37], v[178:181], v[194:197], v[34:37]
	v_mfma_f32_16x16x32_bf16 v[26:29], v[170:173], v[206:209], v[26:29]
	v_mfma_f32_16x16x32_bf16 v[18:21], v[178:181], v[206:209], v[18:21]
	v_mfma_f32_16x16x32_bf16 v[10:13], v[170:173], v[224:227], v[10:13]
	v_mfma_f32_16x16x32_bf16 v[2:5], v[178:181], v[224:227], v[2:5]
	s_setprio 0
	s_barrier
	s_add_i32 s41, 0, 0x18000
	v_add_u32_e32 v146, s41, v148
	s_add_i32 s43, 0, 0x1c000
	ds_read_b128 v[142:145], v146
	ds_read_b128 v[154:157], v146 offset:1024
	ds_read_b128 v[158:161], v146 offset:2048
	ds_read_b128 v[162:165], v146 offset:3072
	v_add_u32_e32 v146, s43, v148
	ds_read_b128 v[166:169], v146
	ds_read_b128 v[170:173], v146 offset:1024
	ds_read_b128 v[174:177], v146 offset:2048
	ds_read_b128 v[178:181], v146 offset:3072
	s_add_u32 s14, s20, 0x40000
	s_addc_u32 s15, s21, 0
	s_mov_b32 m0, s48
	v_lshl_add_u64 v[234:235], s[14:15], 0, v[134:135]
	ds_read_b128 v[182:185], v152 offset:32768
	ds_read_b128 v[186:189], v152 offset:33792
	ds_read_b128 v[190:193], v152 offset:34816
	ds_read_b128 v[194:197], v152 offset:35840
	ds_read_b128 v[198:201], v152 offset:36864
	ds_read_b128 v[206:209], v152 offset:37888
	ds_read_b128 v[210:213], v152 offset:38912
	ds_read_b128 v[224:227], v152 offset:39936
	global_load_lds_dwordx4 v[234:235], off
	v_lshl_add_u64 v[234:235], s[14:15], 0, v[132:133]
	s_mov_b32 m0, s49
	s_nop 0
	global_load_lds_dwordx4 v[234:235], off
	s_waitcnt vmcnt(8)
	s_waitcnt lgkmcnt(0)
	s_barrier
	s_setprio 1
	s_waitcnt lgkmcnt(0)
	v_mfma_f32_16x16x32_bf16 v[126:129], v[142:145], v[182:185], v[126:129]
	v_mfma_f32_16x16x32_bf16 v[118:121], v[158:161], v[182:185], v[118:121]
	v_mfma_f32_16x16x32_bf16 v[110:113], v[142:145], v[190:193], v[110:113]
	v_mfma_f32_16x16x32_bf16 v[102:105], v[158:161], v[190:193], v[102:105]
	v_mfma_f32_16x16x32_bf16 v[94:97], v[142:145], v[198:201], v[94:97]
	v_mfma_f32_16x16x32_bf16 v[86:89], v[158:161], v[198:201], v[86:89]
	v_mfma_f32_16x16x32_bf16 v[78:81], v[142:145], v[210:213], v[78:81]
	v_mfma_f32_16x16x32_bf16 v[70:73], v[158:161], v[210:213], v[70:73]
	v_mfma_f32_16x16x32_bf16 v[126:129], v[154:157], v[186:189], v[126:129]
	v_mfma_f32_16x16x32_bf16 v[118:121], v[162:165], v[186:189], v[118:121]
	v_mfma_f32_16x16x32_bf16 v[110:113], v[154:157], v[194:197], v[110:113]
	v_mfma_f32_16x16x32_bf16 v[102:105], v[162:165], v[194:197], v[102:105]
	v_mfma_f32_16x16x32_bf16 v[94:97], v[154:157], v[206:209], v[94:97]
	v_mfma_f32_16x16x32_bf16 v[86:89], v[162:165], v[206:209], v[86:89]
	v_mfma_f32_16x16x32_bf16 v[78:81], v[154:157], v[224:227], v[78:81]
	v_mfma_f32_16x16x32_bf16 v[70:73], v[162:165], v[224:227], v[70:73]
	v_mfma_f32_16x16x32_bf16 v[122:125], v[166:169], v[182:185], v[122:125]
	v_mfma_f32_16x16x32_bf16 v[114:117], v[174:177], v[182:185], v[114:117]
	v_mfma_f32_16x16x32_bf16 v[106:109], v[166:169], v[190:193], v[106:109]
	v_mfma_f32_16x16x32_bf16 v[98:101], v[174:177], v[190:193], v[98:101]
	v_mfma_f32_16x16x32_bf16 v[90:93], v[166:169], v[198:201], v[90:93]
	v_mfma_f32_16x16x32_bf16 v[82:85], v[174:177], v[198:201], v[82:85]
	v_mfma_f32_16x16x32_bf16 v[74:77], v[166:169], v[210:213], v[74:77]
	v_mfma_f32_16x16x32_bf16 v[66:69], v[174:177], v[210:213], v[66:69]
	v_mfma_f32_16x16x32_bf16 v[122:125], v[170:173], v[186:189], v[122:125]
	v_mfma_f32_16x16x32_bf16 v[114:117], v[178:181], v[186:189], v[114:117]
	v_mfma_f32_16x16x32_bf16 v[106:109], v[170:173], v[194:197], v[106:109]
	v_mfma_f32_16x16x32_bf16 v[98:101], v[178:181], v[194:197], v[98:101]
	v_mfma_f32_16x16x32_bf16 v[90:93], v[170:173], v[206:209], v[90:93]
	v_mfma_f32_16x16x32_bf16 v[82:85], v[178:181], v[206:209], v[82:85]
	v_mfma_f32_16x16x32_bf16 v[74:77], v[170:173], v[224:227], v[74:77]
	v_mfma_f32_16x16x32_bf16 v[66:69], v[178:181], v[224:227], v[66:69]
	s_setprio 0
	s_barrier
; #define PG8_STAGE(bufoff, gbase, voff) do { _Pragma("unroll") for (int _i = 0; _i < 2; ++_i) \
;         __builtin_amdgcn_global_load_lds((const unsigned*)((const char*)(gbase) + (voff)[_i]), (PG8_LAS unsigned*)(lds + (bufoff) + ldsw + _i * 8192), 16, 0, 0); } while (0)
; #define PG8_LDA(dst, b, h) do { _Pragma("unroll") for (int m = 0; m < 4; ++m) _Pragma("unroll") for (int k = 0; k < 2; ++k) dst[m][k] = *(const PG8_LAS bf16x8*)(lds + PG8_SA(b, h) + aoff + m * 2048 + k * 1024); } while (0)
; #define PG8_MMA(ai, bj, At, Bt) do { __builtin_amdgcn_s_setprio(1); _Pragma("unroll") for (int m = 0; m < 4; ++m) _Pragma("unroll") for (int n = 0; n < 2; ++n) _Pragma("unroll") for (int k = 0; k < 2; ++k) \
;         acc[ai][bj][m][n] = __builtin_amdgcn_mfma_f32_16x16x32_bf16(Bt[n][k], At[m][k], acc[ai][bj][m][n], 0, 0, 0); __builtin_amdgcn_s_setprio(0); } while (0)
; #define PG8_WAIT_V(n) asm volatile("s_waitcnt vmcnt(" #n ")" ::: "memory")
; #define PG8_WAIT_L(n) asm volatile("s_waitcnt lgkmcnt(" #n ")" ::: "memory")
; #define PG8_BAR __builtin_amdgcn_s_barrier()
; #define PG8_SCHED __builtin_amdgcn_sched_barrier(0)
; template <class Epi, class Sched, bool ALIGN_EPI = false, bool SP2 = false>
; __device__ __forceinline__ void gemm_phase(PG8_LAS unsigned char* lds, const Gemm g, const Sched& S, const Epi& E) {
;     ...
;             PG8_LDA(At, 1, 1); PG8_STAGE(PG8_SB(1, 0), b3, voffB); PG8_STAGE(PG8_SB(1, 1), b3 + hstep, voffB); PG8_STAGE(PG8_SA(1, 0), a3, voffA);
;             PG8_WAIT_V(8); PG8_WAIT_L(0); PG8_BAR; PG8_MMA(1, 0, At, B0); PG8_MMA(1, 1, At, B1); PG8_BAR; PG8_SCHED;
	s_add_i32 s14, s41, s22
	v_lshl_add_u64 v[202:203], v[202:203], 0, s[24:25]
	s_mov_b32 m0, s14
	ds_read_b128 v[182:185], v152 offset:49152
	ds_read_b128 v[186:189], v152 offset:50176
	ds_read_b128 v[190:193], v152 offset:51200
	ds_read_b128 v[194:197], v152 offset:52224
	ds_read_b128 v[198:201], v152 offset:53248
	ds_read_b128 v[206:209], v152 offset:54272
	ds_read_b128 v[210:213], v152 offset:55296
	ds_read_b128 v[224:227], v152 offset:56320
	global_load_lds_dwordx4 v[202:203], off
	s_add_i32 m0, s14, 0x2000
	s_add_u32 s4, s4, 0x40080
	v_lshl_add_u64 v[202:203], v[228:229], 0, s[24:25]
	s_addc_u32 s5, s5, 0
	s_add_i32 s14, s43, s22
	global_load_lds_dwordx4 v[202:203], off
	v_lshl_add_u64 v[202:203], s[4:5], 0, v[0:1]
	s_mov_b32 m0, s14
	s_nop 0
	global_load_lds_dwordx4 v[202:203], off
	v_lshl_add_u64 v[202:203], s[4:5], 0, v[130:131]
	s_add_i32 m0, s14, 0x2000
	s_nop 0
	global_load_lds_dwordx4 v[202:203], off
	v_lshl_add_u64 v[202:203], v[230:231], 0, s[24:25]
	s_mov_b32 m0, s50
	s_nop 0
	global_load_lds_dwordx4 v[202:203], off
	v_lshl_add_u64 v[202:203], v[232:233], 0, s[24:25]
	s_mov_b32 m0, s51
	s_nop 0
	global_load_lds_dwordx4 v[202:203], off
	s_waitcnt vmcnt(8)
	s_waitcnt lgkmcnt(0)
	s_barrier
	s_setprio 1
	s_waitcnt lgkmcnt(0)
	v_mfma_f32_16x16x32_bf16 v[62:65], v[142:145], v[182:185], v[62:65]
	v_mfma_f32_16x16x32_bf16 v[54:57], v[158:161], v[182:185], v[54:57]
	v_mfma_f32_16x16x32_bf16 v[46:49], v[142:145], v[190:193], v[46:49]
	v_mfma_f32_16x16x32_bf16 v[38:41], v[158:161], v[190:193], v[38:41]
	v_mfma_f32_16x16x32_bf16 v[30:33], v[142:145], v[198:201], v[30:33]
	v_mfma_f32_16x16x32_bf16 v[22:25], v[158:161], v[198:201], v[22:25]
	v_mfma_f32_16x16x32_bf16 v[14:17], v[142:145], v[210:213], v[14:17]
	v_mfma_f32_16x16x32_bf16 v[6:9], v[158:161], v[210:213], v[6:9]
	v_mfma_f32_16x16x32_bf16 v[62:65], v[154:157], v[186:189], v[62:65]
	v_mfma_f32_16x16x32_bf16 v[54:57], v[162:165], v[186:189], v[54:57]
	v_mfma_f32_16x16x32_bf16 v[46:49], v[154:157], v[194:197], v[46:49]
	v_mfma_f32_16x16x32_bf16 v[38:41], v[162:165], v[194:197], v[38:41]
	v_mfma_f32_16x16x32_bf16 v[30:33], v[154:157], v[206:209], v[30:33]
	v_mfma_f32_16x16x32_bf16 v[22:25], v[162:165], v[206:209], v[22:25]
	v_mfma_f32_16x16x32_bf16 v[14:17], v[154:157], v[224:227], v[14:17]
	v_mfma_f32_16x16x32_bf16 v[6:9], v[162:165], v[224:227], v[6:9]
	v_mfma_f32_16x16x32_bf16 v[58:61], v[166:169], v[182:185], v[58:61]
	v_mfma_f32_16x16x32_bf16 v[50:53], v[174:177], v[182:185], v[50:53]
	v_mfma_f32_16x16x32_bf16 v[42:45], v[166:169], v[190:193], v[42:45]
	v_mfma_f32_16x16x32_bf16 v[34:37], v[174:177], v[190:193], v[34:37]
	v_mfma_f32_16x16x32_bf16 v[26:29], v[166:169], v[198:201], v[26:29]
	v_mfma_f32_16x16x32_bf16 v[18:21], v[174:177], v[198:201], v[18:21]
	v_mfma_f32_16x16x32_bf16 v[10:13], v[166:169], v[210:213], v[10:13]
	v_mfma_f32_16x16x32_bf16 v[2:5], v[174:177], v[210:213], v[2:5]
	v_mfma_f32_16x16x32_bf16 v[58:61], v[170:173], v[186:189], v[58:61]
	v_mfma_f32_16x16x32_bf16 v[50:53], v[178:181], v[186:189], v[50:53]
	v_mfma_f32_16x16x32_bf16 v[42:45], v[170:173], v[194:197], v[42:45]
	v_mfma_f32_16x16x32_bf16 v[34:37], v[178:181], v[194:197], v[34:37]
	v_mfma_f32_16x16x32_bf16 v[26:29], v[170:173], v[206:209], v[26:29]
	v_mfma_f32_16x16x32_bf16 v[18:21], v[178:181], v[206:209], v[18:21]
	v_mfma_f32_16x16x32_bf16 v[10:13], v[170:173], v[224:227], v[10:13]
	v_mfma_f32_16x16x32_bf16 v[2:5], v[178:181], v[224:227], v[2:5]
	s_setprio 0
	s_barrier
	s_add_i32 s35, s35, 2
	s_add_u32 s0, s0, 0x100
	s_addc_u32 s1, s1, 0
	s_add_u32 s29, s29, 0x100
	s_addc_u32 s34, s34, 0
	s_cmp_gt_u32 s35, 13
	s_cbranch_scc0 .LBB0_535
; __device__ __forceinline__ float sx(float v, int mask, int lane) { return __int_as_float(__builtin_amdgcn_ds_bpermute((lane ^ mask) << 2, __float_as_int(v))); }
; __device__ __forceinline__ float row_rs(const float* ss, int row, int fq, int fr) {
;     ...
;     return 1.0f;
;     ...
;     const f32x4 a = *(const f32x4*)(ss + (size_t)row * 16 + 4 * fq);
;     float s = (a[0] + a[1]) + (a[2] + a[3]);
;     const int ln = fq * 16 + fr; s += sx(s, 16, ln); s += sx(s, 32, ln);
;     return 1.0f / sqrtf(s * (1.0f / D) + RMS_EPS);
;     __device__ __forceinline__ void operator()(const f32x4 (&acc)[2][2][4][2], const Unit& u, int wr, int wc, int fr, int fq) const {
;         const int row0 = u.pm * BM + wr * 64 + fr, col0 = u.pn * HALF + wc * 32 + 8 * fq;
; #pragma unroll
;         for (int ai = 0; ai < 2; ++ai)
; #pragma unroll
;             for (int m = 0; m < 4; ++m) { const int row = row0 + ai * HALF + m * 16; const float rs = row_rs(ss, row, fq, fr);
	v_lshl_add_u32 v142, s3, 8, v147
	v_ashrrev_i32_e32 v143, 31, v142
	v_lshlrev_b64 v[144:145], 6, v[142:143]
	s_mov_b32 s4, 0x2000
	s_mov_b32 s5, 0
	v_lshl_add_u64 v[144:145], v[136:137], 0, v[144:145]
	v_lshl_add_u64 v[228:229], v[144:145], 0, s[4:5]
	global_load_dwordx4 v[154:157], v[144:145], off
	global_load_dwordx4 v[158:161], v[144:145], off offset:1024
	global_load_dwordx4 v[162:165], v[144:145], off offset:2048
	global_load_dwordx4 v[166:169], v[144:145], off offset:3072
	global_load_dwordx4 v[170:173], v[228:229], off
	global_load_dwordx4 v[174:177], v[228:229], off offset:1024
	global_load_dwordx4 v[178:181], v[228:229], off offset:2048
	global_load_dwordx4 v[182:185], v[228:229], off offset:3072
	v_mul_u32_u24_e32 v224, 0x1600, v142
	v_lshl_or_b32 v226, s2, 7, v151
	v_lshl_add_u32 v224, v226, 1, v224
	s_waitcnt vmcnt(7)
	v_add_f32_e32 v155, v155, v154
	v_add_f32_e32 v156, v156, v157
	s_waitcnt vmcnt(6)
	v_add_f32_e32 v159, v159, v158
	v_add_f32_e32 v160, v160, v161
	s_waitcnt vmcnt(5)
	v_add_f32_e32 v163, v163, v162
	v_add_f32_e32 v164, v164, v165
	s_waitcnt vmcnt(4)
	v_add_f32_e32 v167, v167, v166
	v_add_f32_e32 v168, v168, v169
	s_waitcnt vmcnt(3)
	v_add_f32_e32 v171, v171, v170
	v_add_f32_e32 v172, v172, v173
	s_waitcnt vmcnt(2)
	v_add_f32_e32 v175, v175, v174
	v_add_f32_e32 v176, v176, v177
	s_waitcnt vmcnt(1)
	v_add_f32_e32 v179, v179, v178
	v_add_f32_e32 v180, v180, v181
	s_waitcnt vmcnt(0)
	v_add_f32_e32 v183, v183, v182
	v_add_f32_e32 v184, v184, v185
	v_add_f32_e32 v154, v155, v156
	v_add_f32_e32 v158, v159, v160
	v_add_f32_e32 v162, v163, v164
	v_add_f32_e32 v166, v167, v168
	v_add_f32_e32 v170, v171, v172
	v_add_f32_e32 v174, v175, v176
	v_add_f32_e32 v178, v179, v180
	v_add_f32_e32 v182, v183, v184
	ds_bpermute_b32 v155, v149, v154
	ds_bpermute_b32 v159, v149, v158
	ds_bpermute_b32 v163, v149, v162
	ds_bpermute_b32 v167, v149, v166
	ds_bpermute_b32 v171, v149, v170
	ds_bpermute_b32 v175, v149, v174
	ds_bpermute_b32 v179, v149, v178
	ds_bpermute_b32 v183, v149, v182
	s_waitcnt lgkmcnt(7)
	v_add_f32_e32 v154, v154, v155
	s_waitcnt lgkmcnt(6)
	v_add_f32_e32 v158, v158, v159
	s_waitcnt lgkmcnt(5)
	v_add_f32_e32 v162, v162, v163
	s_waitcnt lgkmcnt(4)
	v_add_f32_e32 v166, v166, v167
	s_waitcnt lgkmcnt(3)
	v_add_f32_e32 v170, v170, v171
	s_waitcnt lgkmcnt(2)
	v_add_f32_e32 v174, v174, v175
	s_waitcnt lgkmcnt(1)
	v_add_f32_e32 v178, v178, v179
	s_waitcnt lgkmcnt(0)
	v_add_f32_e32 v182, v182, v183
	ds_bpermute_b32 v155, v150, v154
	ds_bpermute_b32 v159, v150, v158
	ds_bpermute_b32 v163, v150, v162
	ds_bpermute_b32 v167, v150, v166
	ds_bpermute_b32 v171, v150, v170
	ds_bpermute_b32 v175, v150, v174
	ds_bpermute_b32 v179, v150, v178
	ds_bpermute_b32 v183, v150, v182
	s_waitcnt lgkmcnt(7)
	v_add_f32_e32 v154, v154, v155
	s_waitcnt lgkmcnt(6)
	v_add_f32_e32 v158, v158, v159
	s_waitcnt lgkmcnt(5)
	v_add_f32_e32 v162, v162, v163
	s_waitcnt lgkmcnt(4)
	v_add_f32_e32 v166, v166, v167
	s_waitcnt lgkmcnt(3)
	v_add_f32_e32 v170, v170, v171
	s_waitcnt lgkmcnt(2)
	v_add_f32_e32 v174, v174, v175
	s_waitcnt lgkmcnt(1)
	v_add_f32_e32 v178, v178, v179
	s_waitcnt lgkmcnt(0)
	v_add_f32_e32 v182, v182, v183
	v_fmamk_f32 v154, v154, 0x3a800000, v215
	v_fmamk_f32 v158, v158, 0x3a800000, v215
	v_fmamk_f32 v162, v162, 0x3a800000, v215
	v_fmamk_f32 v166, v166, 0x3a800000, v215
	v_fmamk_f32 v170, v170, 0x3a800000, v215
	v_fmamk_f32 v174, v174, 0x3a800000, v215
	v_fmamk_f32 v178, v178, 0x3a800000, v215
	v_fmamk_f32 v182, v182, 0x3a800000, v215
	v_rsq_f32_e32 v186, v154
	v_rsq_f32_e32 v187, v158
	v_rsq_f32_e32 v188, v162
	v_rsq_f32_e32 v189, v166
	v_rsq_f32_e32 v190, v170
	v_rsq_f32_e32 v191, v174
	v_rsq_f32_e32 v192, v178
	v_rsq_f32_e32 v193, v182
	s_and_b64 vcc, exec, s[8:9]
	s_cbranch_vccz .Lswi_nobar
	s_barrier

; #define PG8_STAGE(bufoff, gbase, voff) do { _Pragma("unroll") for (int _i = 0; _i < 2; ++_i) \
;         __builtin_amdgcn_global_load_lds((const unsigned*)((const char*)(gbase) + (voff)[_i]), (PG8_LAS unsigned*)(lds + (bufoff) + ldsw + _i * 8192), 16, 0, 0); } while (0)
; #define PG8_LDA(dst, b, h) do { _Pragma("unroll") for (int m = 0; m < 4; ++m) _Pragma("unroll") for (int k = 0; k < 2; ++k) dst[m][k] = *(const PG8_LAS bf16x8*)(lds + PG8_SA(b, h) + aoff + m * 2048 + k * 1024); } while (0)
; #define PG8_LDB(dst, b, h) do { _Pragma("unroll") for (int n = 0; n < 2; ++n) _Pragma("unroll") for (int k = 0; k < 2; ++k) dst[n][k] = *(const PG8_LAS bf16x8*)(lds + PG8_SB(b, h) + boff + n * 2048 + k * 1024); } while (0)
; #define PG8_MMA(ai, bj, At, Bt) do { __builtin_amdgcn_s_setprio(1); _Pragma("unroll") for (int m = 0; m < 4; ++m) _Pragma("unroll") for (int n = 0; n < 2; ++n) _Pragma("unroll") for (int k = 0; k < 2; ++k) \
;         acc[ai][bj][m][n] = __builtin_amdgcn_mfma_f32_16x16x32_bf16(Bt[n][k], At[m][k], acc[ai][bj][m][n], 0, 0, 0); __builtin_amdgcn_s_setprio(0); } while (0)
; #define PG8_WAIT_V(n) asm volatile("s_waitcnt vmcnt(" #n ")" ::: "memory")
; #define PG8_WAIT_L(n) asm volatile("s_waitcnt lgkmcnt(" #n ")" ::: "memory")
; #define PG8_BAR __builtin_amdgcn_s_barrier()
; #define PG8_SCHED __builtin_amdgcn_sched_barrier(0)
; template <class Epi, class Sched, bool ALIGN_EPI = false, bool SP2 = false>
; __device__ __forceinline__ void gemm_phase(PG8_LAS unsigned char* lds, const Gemm g, const Sched& S, const Epi& E) {
;     ...
;             PG8_LDB(B0, 0, 0); PG8_LDB(B1, 0, 1); PG8_SCHED; PG8_LDA(At, 0, 0); PG8_STAGE(PG8_SA(1, 1), a1 + hstep, voffA);
;             PG8_WAIT_V(8); PG8_WAIT_L(0); PG8_BAR; PG8_MMA(0, 0, At, B0); PG8_MMA(0, 1, At, B1); PG8_BAR; PG8_SCHED;
;             PG8_LDA(At, 0, 1); PG8_STAGE(PG8_SB(0, 0), b2, voffB); PG8_STAGE(PG8_SB(0, 1), b2 + hstep, voffB); PG8_STAGE(PG8_SA(0, 0), a2, voffA);
;             PG8_WAIT_V(8); PG8_WAIT_L(0); PG8_BAR; PG8_MMA(1, 0, At, B0); PG8_MMA(1, 1, At, B1); PG8_BAR; PG8_SCHED;
.LBB0_553:
	s_add_u32 s4, s0, 0xfffc0080
	s_addc_u32 s5, s1, -1
	s_add_i32 s14, 0, 0x10000
	s_cmp_eq_u32 s34, 12
	s_cselect_b32 s21, s3, s5
	s_cselect_b32 s20, s10, s4
	s_cselect_b32 s5, s11, s29
	s_cselect_b32 s4, s12, s13
	s_add_i32 s15, 0, 0x14000
	v_add_u32_e32 v166, s14, v151
	v_add_u32_e32 v182, s15, v151
	ds_read_b128 v[142:145], v166
	ds_read_b128 v[146:149], v166 offset:1024
	ds_read_b128 v[162:165], v166 offset:2048
	ds_read_b128 v[166:169], v166 offset:3072
	ds_read_b128 v[170:173], v182
	ds_read_b128 v[174:177], v182 offset:1024
	ds_read_b128 v[178:181], v182 offset:2048
	ds_read_b128 v[182:185], v182 offset:3072
	v_lshl_add_u64 v[190:191], s[0:1], 0, v[138:139]
	s_add_i32 m0, s23, 0xc000
	ds_read_b128 v[186:189], v161
	ds_read_b128 v[200:203], v161 offset:1024
	ds_read_b128 v[206:209], v161 offset:2048
	ds_read_b128 v[210:213], v161 offset:3072
	ds_read_b128 v[224:227], v161 offset:4096
	ds_read_b128 v[228:231], v161 offset:5120
	ds_read_b128 v[232:235], v161 offset:6144
	ds_read_b128 v[236:239], v161 offset:7168
	global_load_lds_dwordx4 v[190:191], off
	v_lshl_add_u64 v[190:191], s[0:1], 0, v[140:141]
	s_add_i32 m0, s23, 0xe000
	s_nop 0
	global_load_lds_dwordx4 v[190:191], off
	s_waitcnt vmcnt(8)
	s_waitcnt lgkmcnt(0)
	s_barrier
	s_setprio 1
	s_waitcnt lgkmcnt(0)
	v_mfma_f32_16x16x32_bf16 v[126:129], v[142:145], v[186:189], v[126:129]
	v_mfma_f32_16x16x32_bf16 v[122:125], v[162:165], v[186:189], v[122:125]
	v_mfma_f32_16x16x32_bf16 v[110:113], v[142:145], v[206:209], v[110:113]
	v_mfma_f32_16x16x32_bf16 v[106:109], v[162:165], v[206:209], v[106:109]
	v_mfma_f32_16x16x32_bf16 v[94:97], v[142:145], v[224:227], v[94:97]
	v_mfma_f32_16x16x32_bf16 v[90:93], v[162:165], v[224:227], v[90:93]
	v_mfma_f32_16x16x32_bf16 v[78:81], v[142:145], v[232:235], v[78:81]
	v_mfma_f32_16x16x32_bf16 v[74:77], v[162:165], v[232:235], v[74:77]
	v_mfma_f32_16x16x32_bf16 v[126:129], v[146:149], v[200:203], v[126:129]
	v_mfma_f32_16x16x32_bf16 v[122:125], v[166:169], v[200:203], v[122:125]
	v_mfma_f32_16x16x32_bf16 v[110:113], v[146:149], v[210:213], v[110:113]
	v_mfma_f32_16x16x32_bf16 v[106:109], v[166:169], v[210:213], v[106:109]
	v_mfma_f32_16x16x32_bf16 v[94:97], v[146:149], v[228:231], v[94:97]
	v_mfma_f32_16x16x32_bf16 v[90:93], v[166:169], v[228:231], v[90:93]
	v_mfma_f32_16x16x32_bf16 v[78:81], v[146:149], v[236:239], v[78:81]
	v_mfma_f32_16x16x32_bf16 v[74:77], v[166:169], v[236:239], v[74:77]
	v_mfma_f32_16x16x32_bf16 v[118:121], v[170:173], v[186:189], v[118:121]
	v_mfma_f32_16x16x32_bf16 v[114:117], v[178:181], v[186:189], v[114:117]
	v_mfma_f32_16x16x32_bf16 v[102:105], v[170:173], v[206:209], v[102:105]
	v_mfma_f32_16x16x32_bf16 v[98:101], v[178:181], v[206:209], v[98:101]
	v_mfma_f32_16x16x32_bf16 v[86:89], v[170:173], v[224:227], v[86:89]
	v_mfma_f32_16x16x32_bf16 v[82:85], v[178:181], v[224:227], v[82:85]
	v_mfma_f32_16x16x32_bf16 v[70:73], v[170:173], v[232:235], v[70:73]
	v_mfma_f32_16x16x32_bf16 v[66:69], v[178:181], v[232:235], v[66:69]
	v_mfma_f32_16x16x32_bf16 v[118:121], v[174:177], v[200:203], v[118:121]
	v_mfma_f32_16x16x32_bf16 v[114:117], v[182:185], v[200:203], v[114:117]
	v_mfma_f32_16x16x32_bf16 v[102:105], v[174:177], v[210:213], v[102:105]
	v_mfma_f32_16x16x32_bf16 v[98:101], v[182:185], v[210:213], v[98:101]
	v_mfma_f32_16x16x32_bf16 v[86:89], v[174:177], v[228:231], v[86:89]
	v_mfma_f32_16x16x32_bf16 v[82:85], v[182:185], v[228:231], v[82:85]
	v_mfma_f32_16x16x32_bf16 v[70:73], v[174:177], v[236:239], v[70:73]
	v_mfma_f32_16x16x32_bf16 v[66:69], v[182:185], v[236:239], v[66:69]
	s_setprio 0
	s_barrier
	s_add_i32 s14, s14, s22
	v_lshl_add_u64 v[190:191], s[4:5], 0, v[0:1]
	s_mov_b32 m0, s14
	ds_read_b128 v[186:189], v161 offset:16384
	ds_read_b128 v[200:203], v161 offset:17408
	ds_read_b128 v[206:209], v161 offset:18432
	ds_read_b128 v[210:213], v161 offset:19456
	ds_read_b128 v[224:227], v161 offset:20480
	ds_read_b128 v[228:231], v161 offset:21504
	ds_read_b128 v[232:235], v161 offset:22528
	ds_read_b128 v[236:239], v161 offset:23552
	global_load_lds_dwordx4 v[190:191], off
	s_add_i32 m0, s14, 0x2000
	s_add_u32 s42, s4, 0x40000
	v_lshl_add_u64 v[192:193], s[4:5], 0, v[130:131]
	s_addc_u32 s43, s5, 0
	s_add_i32 s14, s15, s22
	global_load_lds_dwordx4 v[192:193], off
	v_lshl_add_u64 v[194:195], s[42:43], 0, v[0:1]
	s_mov_b32 m0, s14
	v_lshl_add_u64 v[196:197], s[20:21], 0, v[132:133]
	global_load_lds_dwordx4 v[194:195], off
	v_lshl_add_u64 v[194:195], s[42:43], 0, v[130:131]
	s_add_i32 m0, s14, 0x2000
	s_nop 0
	global_load_lds_dwordx4 v[194:195], off
	v_lshl_add_u64 v[194:195], s[20:21], 0, v[134:135]
	s_mov_b32 m0, s23
	s_nop 0
	global_load_lds_dwordx4 v[194:195], off
	s_mov_b32 m0, s26
	s_nop 0
	global_load_lds_dwordx4 v[196:197], off
	s_waitcnt vmcnt(8)
	s_waitcnt lgkmcnt(0)
	s_barrier
; #define PG8_STAGE(bufoff, gbase, voff) do { _Pragma("unroll") for (int _i = 0; _i < 2; ++_i) \
;         __builtin_amdgcn_global_load_lds((const unsigned*)((const char*)(gbase) + (voff)[_i]), (PG8_LAS unsigned*)(lds + (bufoff) + ldsw + _i * 8192), 16, 0, 0); } while (0)
; #define PG8_LDA(dst, b, h) do { _Pragma("unroll") for (int m = 0; m < 4; ++m) _Pragma("unroll") for (int k = 0; k < 2; ++k) dst[m][k] = *(const PG8_LAS bf16x8*)(lds + PG8_SA(b, h) + aoff + m * 2048 + k * 1024); } while (0)
; #define PG8_LDB(dst, b, h) do { _Pragma("unroll") for (int n = 0; n < 2; ++n) _Pragma("unroll") for (int k = 0; k < 2; ++k) dst[n][k] = *(const PG8_LAS bf16x8*)(lds + PG8_SB(b, h) + boff + n * 2048 + k * 1024); } while (0)
; #define PG8_MMA(ai, bj, At, Bt) do { __builtin_amdgcn_s_setprio(1); _Pragma("unroll") for (int m = 0; m < 4; ++m) _Pragma("unroll") for (int n = 0; n < 2; ++n) _Pragma("unroll") for (int k = 0; k < 2; ++k) \
;         acc[ai][bj][m][n] = __builtin_amdgcn_mfma_f32_16x16x32_bf16(Bt[n][k], At[m][k], acc[ai][bj][m][n], 0, 0, 0); __builtin_amdgcn_s_setprio(0); } while (0)
; #define PG8_WAIT_V(n) asm volatile("s_waitcnt vmcnt(" #n ")" ::: "memory")
; #define PG8_WAIT_L(n) asm volatile("s_waitcnt lgkmcnt(" #n ")" ::: "memory")
; #define PG8_BAR __builtin_amdgcn_s_barrier()
; #define PG8_SCHED __builtin_amdgcn_sched_barrier(0)
; template <class Epi, class Sched, bool ALIGN_EPI = false, bool SP2 = false>
; __device__ __forceinline__ void gemm_phase(PG8_LAS unsigned char* lds, const Gemm g, const Sched& S, const Epi& E) {
;     ...
;             PG8_WAIT_V(8); PG8_WAIT_L(0); PG8_BAR; PG8_MMA(1, 0, At, B0); PG8_MMA(1, 1, At, B1); PG8_BAR; PG8_SCHED;
;             PG8_LDB(B0, 1, 0); PG8_LDB(B1, 1, 1); PG8_SCHED; PG8_LDA(At, 1, 0); PG8_STAGE(PG8_SA(0, 1), a2 + hstep, voffA);
;             PG8_WAIT_V(8); PG8_WAIT_L(0); PG8_BAR; PG8_MMA(0, 0, At, B0); PG8_MMA(0, 1, At, B1); PG8_BAR; PG8_SCHED;
	s_setprio 1
	s_waitcnt lgkmcnt(0)
	v_mfma_f32_16x16x32_bf16 v[62:65], v[142:145], v[186:189], v[62:65]
	v_mfma_f32_16x16x32_bf16 v[58:61], v[162:165], v[186:189], v[58:61]
	v_mfma_f32_16x16x32_bf16 v[46:49], v[142:145], v[206:209], v[46:49]
	v_mfma_f32_16x16x32_bf16 v[42:45], v[162:165], v[206:209], v[42:45]
	v_mfma_f32_16x16x32_bf16 v[30:33], v[142:145], v[224:227], v[30:33]
	v_mfma_f32_16x16x32_bf16 v[26:29], v[162:165], v[224:227], v[26:29]
	v_mfma_f32_16x16x32_bf16 v[14:17], v[142:145], v[232:235], v[14:17]
	v_mfma_f32_16x16x32_bf16 v[10:13], v[162:165], v[232:235], v[10:13]
	v_mfma_f32_16x16x32_bf16 v[62:65], v[146:149], v[200:203], v[62:65]
	v_mfma_f32_16x16x32_bf16 v[58:61], v[166:169], v[200:203], v[58:61]
	v_mfma_f32_16x16x32_bf16 v[46:49], v[146:149], v[210:213], v[46:49]
	v_mfma_f32_16x16x32_bf16 v[42:45], v[166:169], v[210:213], v[42:45]
	v_mfma_f32_16x16x32_bf16 v[30:33], v[146:149], v[228:231], v[30:33]
	v_mfma_f32_16x16x32_bf16 v[26:29], v[166:169], v[228:231], v[26:29]
	v_mfma_f32_16x16x32_bf16 v[14:17], v[146:149], v[236:239], v[14:17]
	v_mfma_f32_16x16x32_bf16 v[10:13], v[166:169], v[236:239], v[10:13]
	v_mfma_f32_16x16x32_bf16 v[54:57], v[170:173], v[186:189], v[54:57]
	v_mfma_f32_16x16x32_bf16 v[50:53], v[178:181], v[186:189], v[50:53]
	v_mfma_f32_16x16x32_bf16 v[38:41], v[170:173], v[206:209], v[38:41]
	v_mfma_f32_16x16x32_bf16 v[34:37], v[178:181], v[206:209], v[34:37]
	v_mfma_f32_16x16x32_bf16 v[22:25], v[170:173], v[224:227], v[22:25]
	v_mfma_f32_16x16x32_bf16 v[18:21], v[178:181], v[224:227], v[18:21]
	v_mfma_f32_16x16x32_bf16 v[6:9], v[170:173], v[232:235], v[6:9]
	v_mfma_f32_16x16x32_bf16 v[2:5], v[178:181], v[232:235], v[2:5]
	v_mfma_f32_16x16x32_bf16 v[54:57], v[174:177], v[200:203], v[54:57]
	v_mfma_f32_16x16x32_bf16 v[50:53], v[182:185], v[200:203], v[50:53]
	v_mfma_f32_16x16x32_bf16 v[38:41], v[174:177], v[210:213], v[38:41]
	v_mfma_f32_16x16x32_bf16 v[34:37], v[182:185], v[210:213], v[34:37]
	v_mfma_f32_16x16x32_bf16 v[22:25], v[174:177], v[228:231], v[22:25]
	v_mfma_f32_16x16x32_bf16 v[18:21], v[182:185], v[228:231], v[18:21]
	v_mfma_f32_16x16x32_bf16 v[6:9], v[174:177], v[236:239], v[6:9]
	v_mfma_f32_16x16x32_bf16 v[2:5], v[182:185], v[236:239], v[2:5]
	s_setprio 0
	s_barrier
	s_add_i32 s14, 0, 0x18000
	s_add_i32 s15, 0, 0x1c000
	v_add_u32_e32 v166, s14, v151
	v_add_u32_e32 v182, s15, v151
	ds_read_b128 v[142:145], v166
	ds_read_b128 v[146:149], v166 offset:1024
	ds_read_b128 v[162:165], v166 offset:2048
	ds_read_b128 v[166:169], v166 offset:3072
	ds_read_b128 v[170:173], v182
	ds_read_b128 v[174:177], v182 offset:1024
	ds_read_b128 v[178:181], v182 offset:2048
	ds_read_b128 v[182:185], v182 offset:3072
	s_add_u32 s20, s20, 0x40000
	s_addc_u32 s21, s21, 0
	s_mov_b32 m0, s30
	v_lshl_add_u64 v[198:199], s[20:21], 0, v[134:135]
	ds_read_b128 v[186:189], v161 offset:32768
	ds_read_b128 v[200:203], v161 offset:33792
	ds_read_b128 v[206:209], v161 offset:34816
	ds_read_b128 v[210:213], v161 offset:35840
	ds_read_b128 v[224:227], v161 offset:36864
	ds_read_b128 v[228:231], v161 offset:37888
	ds_read_b128 v[232:235], v161 offset:38912
	ds_read_b128 v[236:239], v161 offset:39936
	global_load_lds_dwordx4 v[198:199], off
	v_lshl_add_u64 v[198:199], s[20:21], 0, v[132:133]
	s_mov_b32 m0, s31
	s_nop 0
	global_load_lds_dwordx4 v[198:199], off
	s_waitcnt vmcnt(8)
	s_waitcnt lgkmcnt(0)
	s_barrier
	s_setprio 1
	s_waitcnt lgkmcnt(0)
	v_mfma_f32_16x16x32_bf16 v[126:129], v[142:145], v[186:189], v[126:129]
	v_mfma_f32_16x16x32_bf16 v[122:125], v[162:165], v[186:189], v[122:125]
	v_mfma_f32_16x16x32_bf16 v[110:113], v[142:145], v[206:209], v[110:113]
	v_mfma_f32_16x16x32_bf16 v[106:109], v[162:165], v[206:209], v[106:109]
	v_mfma_f32_16x16x32_bf16 v[94:97], v[142:145], v[224:227], v[94:97]
	v_mfma_f32_16x16x32_bf16 v[90:93], v[162:165], v[224:227], v[90:93]
	v_mfma_f32_16x16x32_bf16 v[78:81], v[142:145], v[232:235], v[78:81]
	v_mfma_f32_16x16x32_bf16 v[74:77], v[162:165], v[232:235], v[74:77]
	v_mfma_f32_16x16x32_bf16 v[126:129], v[146:149], v[200:203], v[126:129]
	v_mfma_f32_16x16x32_bf16 v[122:125], v[166:169], v[200:203], v[122:125]
	v_mfma_f32_16x16x32_bf16 v[110:113], v[146:149], v[210:213], v[110:113]
	v_mfma_f32_16x16x32_bf16 v[106:109], v[166:169], v[210:213], v[106:109]
	v_mfma_f32_16x16x32_bf16 v[94:97], v[146:149], v[228:231], v[94:97]
	v_mfma_f32_16x16x32_bf16 v[90:93], v[166:169], v[228:231], v[90:93]
	v_mfma_f32_16x16x32_bf16 v[78:81], v[146:149], v[236:239], v[78:81]
	v_mfma_f32_16x16x32_bf16 v[74:77], v[166:169], v[236:239], v[74:77]
	v_mfma_f32_16x16x32_bf16 v[118:121], v[170:173], v[186:189], v[118:121]
	v_mfma_f32_16x16x32_bf16 v[114:117], v[178:181], v[186:189], v[114:117]
	v_mfma_f32_16x16x32_bf16 v[102:105], v[170:173], v[206:209], v[102:105]
	v_mfma_f32_16x16x32_bf16 v[98:101], v[178:181], v[206:209], v[98:101]
	v_mfma_f32_16x16x32_bf16 v[86:89], v[170:173], v[224:227], v[86:89]
	v_mfma_f32_16x16x32_bf16 v[82:85], v[178:181], v[224:227], v[82:85]
	v_mfma_f32_16x16x32_bf16 v[70:73], v[170:173], v[232:235], v[70:73]
	v_mfma_f32_16x16x32_bf16 v[66:69], v[178:181], v[232:235], v[66:69]
	v_mfma_f32_16x16x32_bf16 v[118:121], v[174:177], v[200:203], v[118:121]
	v_mfma_f32_16x16x32_bf16 v[114:117], v[182:185], v[200:203], v[114:117]
	v_mfma_f32_16x16x32_bf16 v[102:105], v[174:177], v[210:213], v[102:105]
	v_mfma_f32_16x16x32_bf16 v[98:101], v[182:185], v[210:213], v[98:101]
	v_mfma_f32_16x16x32_bf16 v[86:89], v[174:177], v[228:231], v[86:89]
	v_mfma_f32_16x16x32_bf16 v[82:85], v[182:185], v[228:231], v[82:85]
	v_mfma_f32_16x16x32_bf16 v[70:73], v[174:177], v[236:239], v[70:73]
	v_mfma_f32_16x16x32_bf16 v[66:69], v[182:185], v[236:239], v[66:69]
	s_setprio 0
	s_barrier
; #define PG8_STAGE(bufoff, gbase, voff) do { _Pragma("unroll") for (int _i = 0; _i < 2; ++_i) \
;         __builtin_amdgcn_global_load_lds((const unsigned*)((const char*)(gbase) + (voff)[_i]), (PG8_LAS unsigned*)(lds + (bufoff) + ldsw + _i * 8192), 16, 0, 0); } while (0)
; #define PG8_LDA(dst, b, h) do { _Pragma("unroll") for (int m = 0; m < 4; ++m) _Pragma("unroll") for (int k = 0; k < 2; ++k) dst[m][k] = *(const PG8_LAS bf16x8*)(lds + PG8_SA(b, h) + aoff + m * 2048 + k * 1024); } while (0)
; #define PG8_MMA(ai, bj, At, Bt) do { __builtin_amdgcn_s_setprio(1); _Pragma("unroll") for (int m = 0; m < 4; ++m) _Pragma("unroll") for (int n = 0; n < 2; ++n) _Pragma("unroll") for (int k = 0; k < 2; ++k) \
;         acc[ai][bj][m][n] = __builtin_amdgcn_mfma_f32_16x16x32_bf16(Bt[n][k], At[m][k], acc[ai][bj][m][n], 0, 0, 0); __builtin_amdgcn_s_setprio(0); } while (0)
; #define PG8_WAIT_V(n) asm volatile("s_waitcnt vmcnt(" #n ")" ::: "memory")
; #define PG8_WAIT_L(n) asm volatile("s_waitcnt lgkmcnt(" #n ")" ::: "memory")
; #define PG8_BAR __builtin_amdgcn_s_barrier()
; #define PG8_SCHED __builtin_amdgcn_sched_barrier(0)
; template <class Epi, class Sched, bool ALIGN_EPI = false, bool SP2 = false>
; __device__ __forceinline__ void gemm_phase(PG8_LAS unsigned char* lds, const Gemm g, const Sched& S, const Epi& E) {
;     ...
;             PG8_LDA(At, 1, 1); PG8_STAGE(PG8_SB(1, 0), b3, voffB); PG8_STAGE(PG8_SB(1, 1), b3 + hstep, voffB); PG8_STAGE(PG8_SA(1, 0), a3, voffA);
;             PG8_WAIT_V(8); PG8_WAIT_L(0); PG8_BAR; PG8_MMA(1, 0, At, B0); PG8_MMA(1, 1, At, B1); PG8_BAR; PG8_SCHED;
;     ...
;         if constexpr (ALIGN_EPI) { if (wr == 0) PG8_BAR; }
	s_add_i32 s14, s14, s22
	v_lshl_add_u64 v[190:191], v[190:191], 0, s[24:25]
	s_mov_b32 m0, s14
	ds_read_b128 v[186:189], v161 offset:49152
	ds_read_b128 v[200:203], v161 offset:50176
	ds_read_b128 v[206:209], v161 offset:51200
	ds_read_b128 v[210:213], v161 offset:52224
	ds_read_b128 v[224:227], v161 offset:53248
	ds_read_b128 v[228:231], v161 offset:54272
	ds_read_b128 v[232:235], v161 offset:55296
	ds_read_b128 v[236:239], v161 offset:56320
	global_load_lds_dwordx4 v[190:191], off
	s_add_i32 m0, s14, 0x2000
	s_add_u32 s4, s4, 0x40080
	v_lshl_add_u64 v[190:191], v[192:193], 0, s[24:25]
	s_addc_u32 s5, s5, 0
	s_add_i32 s14, s15, s22
	global_load_lds_dwordx4 v[190:191], off
	v_lshl_add_u64 v[190:191], s[4:5], 0, v[0:1]
	s_mov_b32 m0, s14
	s_nop 0
	global_load_lds_dwordx4 v[190:191], off
	v_lshl_add_u64 v[190:191], s[4:5], 0, v[130:131]
	s_add_i32 m0, s14, 0x2000
	s_nop 0
	global_load_lds_dwordx4 v[190:191], off
	v_lshl_add_u64 v[190:191], v[194:195], 0, s[24:25]
	s_mov_b32 m0, s56
	s_nop 0
	global_load_lds_dwordx4 v[190:191], off
	v_lshl_add_u64 v[190:191], v[196:197], 0, s[24:25]
	s_mov_b32 m0, s57
	s_nop 0
	global_load_lds_dwordx4 v[190:191], off
	s_waitcnt vmcnt(8)
	s_waitcnt lgkmcnt(0)
	s_barrier
	s_setprio 1
	s_waitcnt lgkmcnt(0)
	v_mfma_f32_16x16x32_bf16 v[62:65], v[142:145], v[186:189], v[62:65]
	v_mfma_f32_16x16x32_bf16 v[58:61], v[162:165], v[186:189], v[58:61]
	v_mfma_f32_16x16x32_bf16 v[46:49], v[142:145], v[206:209], v[46:49]
	v_mfma_f32_16x16x32_bf16 v[42:45], v[162:165], v[206:209], v[42:45]
	v_mfma_f32_16x16x32_bf16 v[30:33], v[142:145], v[224:227], v[30:33]
	v_mfma_f32_16x16x32_bf16 v[26:29], v[162:165], v[224:227], v[26:29]
	v_mfma_f32_16x16x32_bf16 v[14:17], v[142:145], v[232:235], v[14:17]
	v_mfma_f32_16x16x32_bf16 v[10:13], v[162:165], v[232:235], v[10:13]
	v_mfma_f32_16x16x32_bf16 v[62:65], v[146:149], v[200:203], v[62:65]
	v_mfma_f32_16x16x32_bf16 v[58:61], v[166:169], v[200:203], v[58:61]
	v_mfma_f32_16x16x32_bf16 v[46:49], v[146:149], v[210:213], v[46:49]
	v_mfma_f32_16x16x32_bf16 v[42:45], v[166:169], v[210:213], v[42:45]
	v_mfma_f32_16x16x32_bf16 v[30:33], v[146:149], v[228:231], v[30:33]
	v_mfma_f32_16x16x32_bf16 v[26:29], v[166:169], v[228:231], v[26:29]
	v_mfma_f32_16x16x32_bf16 v[14:17], v[146:149], v[236:239], v[14:17]
	v_mfma_f32_16x16x32_bf16 v[10:13], v[166:169], v[236:239], v[10:13]
	v_mfma_f32_16x16x32_bf16 v[54:57], v[170:173], v[186:189], v[54:57]
	v_mfma_f32_16x16x32_bf16 v[50:53], v[178:181], v[186:189], v[50:53]
	v_mfma_f32_16x16x32_bf16 v[38:41], v[170:173], v[206:209], v[38:41]
	v_mfma_f32_16x16x32_bf16 v[34:37], v[178:181], v[206:209], v[34:37]
	v_mfma_f32_16x16x32_bf16 v[22:25], v[170:173], v[224:227], v[22:25]
	v_mfma_f32_16x16x32_bf16 v[18:21], v[178:181], v[224:227], v[18:21]
	v_mfma_f32_16x16x32_bf16 v[6:9], v[170:173], v[232:235], v[6:9]
	v_mfma_f32_16x16x32_bf16 v[2:5], v[178:181], v[232:235], v[2:5]
	v_mfma_f32_16x16x32_bf16 v[54:57], v[174:177], v[200:203], v[54:57]
	v_mfma_f32_16x16x32_bf16 v[50:53], v[182:185], v[200:203], v[50:53]
	v_mfma_f32_16x16x32_bf16 v[38:41], v[174:177], v[210:213], v[38:41]
	v_mfma_f32_16x16x32_bf16 v[34:37], v[182:185], v[210:213], v[34:37]
	v_mfma_f32_16x16x32_bf16 v[22:25], v[174:177], v[228:231], v[22:25]
	v_mfma_f32_16x16x32_bf16 v[18:21], v[182:185], v[228:231], v[18:21]
	v_mfma_f32_16x16x32_bf16 v[6:9], v[174:177], v[236:239], v[6:9]
	v_mfma_f32_16x16x32_bf16 v[2:5], v[182:185], v[236:239], v[2:5]
	s_setprio 0
	s_barrier
	s_add_i32 s34, s34, 2
	s_add_u32 s0, s0, 0x100
	s_addc_u32 s1, s1, 0
	s_add_u32 s13, s13, 0x100
	s_addc_u32 s29, s29, 0
	s_cmp_gt_u32 s34, 13
	s_cbranch_scc0 .LBB0_553
	s_and_b64 vcc, exec, s[44:45]
	s_movk_i32 s10, 0x1800
	s_mov_b32 s11, 0xf800000
	s_cbranch_vccz .LBB0_556
	s_barrier
